# work queues: 2 queue visits instead of 8 when all 8 XCC queues have resident blocks (census count == 8), else the original 8
# baseline (speedup 1.0000x reference)
.LBB0_198:
	s_or_b64 exec, exec, s[4:5]
	s_waitcnt lgkmcnt(0)
	s_barrier
	ds_read_b32 v0, v103
	s_movk_i32 s4, 0x1b0
	s_waitcnt lgkmcnt(0)
	v_cmp_gt_i32_e32 vcc, s4, v0
	v_readfirstlane_b32 s6, v0
	s_mov_b64 s[4:5], 0
	s_cbranch_vccnz .LBB0_201
	v_mov_b32_e32 v0, 0x12004
	ds_read_b32 v0, v0
	s_waitcnt lgkmcnt(0)
	v_readfirstlane_b32 s4, v0
	s_cmp_eq_u32 s4, 8
	s_cselect_b32 s4, 0, 6
	s_cmp_gt_i32 s47, s4
	s_mov_b32 s4, 0
	s_cbranch_scc1 .LBB0_202
	s_add_i32 s4, s37, 1
	s_and_b32 s37, s4, 7
	s_add_i32 s47, s47, 1
	s_cbranch_execnz .LBB0_194
	s_branch .LBB0_203

.LBB0_610:
	s_or_b64 exec, exec, s[28:29]
	s_waitcnt lgkmcnt(0)
	s_barrier
	ds_read_b32 v0, v220
	s_movk_i32 s28, 0x120
	s_waitcnt lgkmcnt(0)
	v_cmp_gt_i32_e32 vcc, s28, v0
	v_readfirstlane_b32 s30, v0
	s_mov_b64 s[28:29], 0
	s_cbranch_vccnz .LBB0_613
	v_mov_b32_e32 v0, 0x12004
	ds_read_b32 v0, v0
	s_waitcnt lgkmcnt(0)
	v_readfirstlane_b32 s28, v0
	s_cmp_eq_u32 s28, 8
	s_cselect_b32 s28, 0, 6
	s_cmp_gt_i32 s63, s28
	s_mov_b32 s28, 0
	s_cbranch_scc1 .LBB0_614
	s_add_i32 s28, s52, 1
	s_and_b32 s52, s28, 7
	s_add_i32 s63, s63, 1
	s_cbranch_execnz .LBB0_606
	s_branch .LBB0_615

.LBB0_814:
	s_or_b64 exec, exec, s[2:3]
	s_waitcnt lgkmcnt(0)
	s_barrier
	ds_read_b32 v0, v178
	s_movk_i32 s2, 0x100
	s_waitcnt lgkmcnt(0)
	v_cmp_gt_i32_e32 vcc, s2, v0
	v_readfirstlane_b32 s33, v0
	s_mov_b64 s[2:3], 0
	s_cbranch_vccnz .LBB0_817
	v_readlane_b32 s33, v248, 10
	v_mov_b32_e32 v0, 0x12004
	ds_read_b32 v0, v0
	s_waitcnt lgkmcnt(0)
	v_readfirstlane_b32 s2, v0
	s_cmp_eq_u32 s2, 8
	s_cselect_b32 s2, 0, 6
	s_cmp_gt_i32 s33, s2
	s_mov_b32 s2, 0
	s_cbranch_scc1 .LBB0_818
	v_readlane_b32 s2, v248, 8
	s_add_i32 s2, s2, 1
	s_and_b32 s2, s2, 7
	v_writelane_b32 v248, s2, 8
	s_mov_b64 s[2:3], -1
	s_branch .LBB0_819

.LBB0_896:
	s_or_b64 exec, exec, s[8:9]
	s_waitcnt lgkmcnt(0)
	s_barrier
	ds_read_b32 v0, v105
	s_mov_b64 s[8:9], 0
	s_waitcnt lgkmcnt(0)
	v_cmp_gt_i32_e32 vcc, s15, v0
	v_readfirstlane_b32 s0, v0
	s_cbranch_vccnz .LBB0_899
	v_mov_b32_e32 v0, 0x12004
	ds_read_b32 v0, v0
	s_waitcnt lgkmcnt(0)
	v_readfirstlane_b32 s0, v0
	s_cmp_eq_u32 s0, 8
	s_cselect_b32 s0, 0, 6
	s_cmp_gt_i32 s20, s0
	s_cbranch_scc1 .LBB0_900
	s_add_i32 s0, s14, 1
	s_and_b32 s14, s0, 7
	s_add_i32 s20, s20, 1
	s_cbranch_execnz .LBB0_892
	s_branch .LBB0_901
